# attention online softmax: the lazy re-reference of the running max now triggers only when a tile max exceeds it by more than 8 (log2 units), so exp2 arguments stay <= 8 (no overflow, same relative pre
# speedup vs baseline: 1.0476x; 1.0476x over previous
.Latt_loop:
	s_waitcnt vmcnt(0)
	s_barrier
	ds_read_b128 v[64:67], v173 offset:24576
	ds_read_b128 v[68:71], v173 offset:28672
	s_mov_b32 m0, s44
	ds_read_b128 v[72:75], v171 offset:24576
	global_load_lds_dwordx4 v200, s[40:41]
	s_add_u32 m0, s44, 0x400
	ds_read_b128 v[76:79], v171 offset:28672
	global_load_lds_dwordx4 v190, s[40:41]
	s_mov_b32 m0, s45
	ds_read_b128 v[216:219], v169 offset:24576
	global_load_lds_dwordx4 v192, s[42:43]
	s_add_u32 m0, s45, 0x400
	ds_read_b128 v[220:223], v169 offset:28672
	global_load_lds_dwordx4 v194, s[42:43]
	s_add_u32 m0, s45, 0x800
	ds_read_b128 v[224:227], v167 offset:24576
	global_load_lds_dwordx4 v196, s[42:43]
	s_add_u32 m0, s45, 0xc00
	ds_read_b128 v[228:231], v167 offset:28672
	global_load_lds_dwordx4 v198, s[42:43]
	ds_read_b128 v[232:235], v173 offset:32768
	ds_read_b128 v[236:239], v173 offset:36864
	ds_read_b128 v[240:243], v173 offset:40960
	ds_read_b128 v[244:247], v173 offset:45056
	s_add_u32 s40, s40, 0x18000
	s_addc_u32 s41, s41, 0
	s_add_u32 s42, s42, 0x80
	s_addc_u32 s43, s43, 0
	s_waitcnt lgkmcnt(11)
	v_mfma_f32_32x32x16_bf16 v[112:127], v[64:67], v[140:143], v[96:111]
	ds_read_b128 v[64:67], v171 offset:32768
	s_waitcnt lgkmcnt(11)
	v_mfma_f32_32x32x16_bf16 v[80:95], v[68:71], v[140:143], v[96:111]
	ds_read_b128 v[68:71], v171 offset:36864
	s_waitcnt lgkmcnt(11)
	v_mfma_f32_32x32x16_bf16 v[112:127], v[72:75], v[136:139], v[112:127]
	ds_read_b128 v[72:75], v171 offset:40960
	s_waitcnt lgkmcnt(11)
	v_mfma_f32_32x32x16_bf16 v[80:95], v[76:79], v[136:139], v[80:95]
	ds_read_b128 v[76:79], v171 offset:45056
	s_waitcnt lgkmcnt(11)
	v_mfma_f32_32x32x16_bf16 v[112:127], v[216:219], v[132:135], v[112:127]
	ds_read_b128 v[216:219], v169 offset:32768
	s_waitcnt lgkmcnt(11)
	v_mfma_f32_32x32x16_bf16 v[80:95], v[220:223], v[132:135], v[80:95]
	ds_read_b128 v[220:223], v169 offset:36864
	s_waitcnt lgkmcnt(11)
	v_mfma_f32_32x32x16_bf16 v[112:127], v[224:227], v[128:131], v[112:127]
	ds_read_b128 v[224:227], v169 offset:40960
	s_waitcnt lgkmcnt(11)
	v_mfma_f32_32x32x16_bf16 v[80:95], v[228:231], v[128:131], v[80:95]
	ds_read_b128 v[228:231], v169 offset:45056
	s_nop 7
	s_nop 3
	v_max3_f32 v175, v112, v113, v114
	v_max3_f32 v177, v115, v116, v117
	v_max3_f32 v179, v118, v119, v120
	v_max3_f32 v181, v121, v122, v123
	v_max3_f32 v248, v124, v125, v126
	v_max3_f32 v249, v127, v80, v81
	v_max3_f32 v250, v82, v83, v84
	v_max3_f32 v251, v85, v86, v87
	v_max3_f32 v253, v88, v89, v90
	v_max3_f32 v254, v91, v92, v93
	v_max_f32_e32 v255, v94, v95
	v_max3_f32 v175, v175, v177, v179
	v_max3_f32 v181, v181, v248, v249
	v_max3_f32 v250, v250, v251, v253
	v_max_f32_e32 v254, v254, v255
	v_max3_f32 v175, v175, v181, v250
	v_max_f32_e32 v175, v175, v254
	v_mov_b32_e32 v177, v175
	s_nop 1
	v_permlane32_swap_b32_e32 v175, v177
	v_max_f32_e32 v175, v175, v177
	v_cmp_lt_f32_e32 vcc, 0x41000000, v175
	s_cbranch_vccnz .Latt_resc_a
.Latt_cont_a:
	v_exp_f32_e32 v112, v112
	v_exp_f32_e32 v113, v113
	v_exp_f32_e32 v114, v114
	v_exp_f32_e32 v115, v115
	v_exp_f32_e32 v116, v116
	v_exp_f32_e32 v117, v117
	v_exp_f32_e32 v118, v118
	v_exp_f32_e32 v119, v119
	v_add_f32_e32 v183, v112, v113
	v_add_f32_e32 v183, v183, v114
	v_add_f32_e32 v183, v183, v115
	v_add_f32_e32 v183, v183, v116
	v_add_f32_e32 v183, v183, v117
	v_add_f32_e32 v183, v183, v118
	v_add_f32_e32 v183, v183, v119
	v_cvt_pk_bf16_f32 v112, v112, v113
	v_cvt_pk_bf16_f32 v113, v114, v115
	v_cvt_pk_bf16_f32 v114, v116, v117
	v_cvt_pk_bf16_f32 v115, v118, v119
	v_exp_f32_e32 v120, v120
	v_exp_f32_e32 v121, v121
	s_waitcnt lgkmcnt(8)
	v_mfma_f32_32x32x16_bf16 v[48:63], v[232:235], v[112:115], v[48:63]
	v_exp_f32_e32 v122, v122
	v_exp_f32_e32 v123, v123
	v_exp_f32_e32 v124, v124
	v_mfma_f32_32x32x16_bf16 v[32:47], v[236:239], v[112:115], v[32:47]
	v_exp_f32_e32 v125, v125
	v_exp_f32_e32 v126, v126
	v_exp_f32_e32 v127, v127
	v_mfma_f32_32x32x16_bf16 v[16:31], v[240:243], v[112:115], v[16:31]
	v_add_f32_e32 v185, v120, v121
	v_add_f32_e32 v185, v185, v122
	v_add_f32_e32 v185, v185, v123
	v_add_f32_e32 v185, v185, v124
	v_add_f32_e32 v185, v185, v125
	v_add_f32_e32 v185, v185, v126
	v_mfma_f32_32x32x16_bf16 v[0:15], v[244:247], v[112:115], v[0:15]
	ds_read_b128 v[232:235], v167 offset:32768
	ds_read_b128 v[236:239], v167 offset:36864
	ds_read_b128 v[240:243], v167 offset:40960
	ds_read_b128 v[244:247], v167 offset:45056
	v_add_f32_e32 v185, v185, v127
	v_cvt_pk_bf16_f32 v116, v120, v121
	v_cvt_pk_bf16_f32 v117, v122, v123
	v_cvt_pk_bf16_f32 v118, v124, v125
	v_cvt_pk_bf16_f32 v119, v126, v127
	s_nop 0
	s_waitcnt lgkmcnt(8)
	v_mfma_f32_32x32x16_bf16 v[48:63], v[64:67], v[116:119], v[48:63]
	v_exp_f32_e32 v80, v80
	v_exp_f32_e32 v81, v81
	v_exp_f32_e32 v82, v82
	v_mfma_f32_32x32x16_bf16 v[32:47], v[68:71], v[116:119], v[32:47]
	v_exp_f32_e32 v83, v83
	v_exp_f32_e32 v84, v84
	v_exp_f32_e32 v85, v85
	v_mfma_f32_32x32x16_bf16 v[16:31], v[72:75], v[116:119], v[16:31]
	v_exp_f32_e32 v86, v86
	v_exp_f32_e32 v87, v87
	v_add_f32_e32 v187, v80, v81
	v_add_f32_e32 v187, v187, v82
	v_mfma_f32_32x32x16_bf16 v[0:15], v[76:79], v[116:119], v[0:15]
	v_add_f32_e32 v187, v187, v83
	v_add_f32_e32 v187, v187, v84
	v_add_f32_e32 v187, v187, v85
	v_add_f32_e32 v187, v187, v86
	v_add_f32_e32 v187, v187, v87
	v_cvt_pk_bf16_f32 v80, v80, v81
	v_cvt_pk_bf16_f32 v81, v82, v83
	v_cvt_pk_bf16_f32 v82, v84, v85
	v_cvt_pk_bf16_f32 v83, v86, v87
	s_nop 0
	s_waitcnt lgkmcnt(4)
	v_mfma_f32_32x32x16_bf16 v[48:63], v[216:219], v[80:83], v[48:63]
	v_exp_f32_e32 v88, v88
	v_exp_f32_e32 v89, v89
	v_exp_f32_e32 v90, v90
	v_mfma_f32_32x32x16_bf16 v[32:47], v[220:223], v[80:83], v[32:47]
	v_exp_f32_e32 v91, v91
	v_exp_f32_e32 v92, v92
	v_exp_f32_e32 v93, v93
	v_mfma_f32_32x32x16_bf16 v[16:31], v[224:227], v[80:83], v[16:31]
	v_exp_f32_e32 v94, v94
	v_exp_f32_e32 v95, v95
	v_add_f32_e32 v215, v88, v89
	v_add_f32_e32 v215, v215, v90
	v_mfma_f32_32x32x16_bf16 v[0:15], v[228:231], v[80:83], v[0:15]
	v_add_f32_e32 v215, v215, v91
	v_add_f32_e32 v215, v215, v92
	v_add_f32_e32 v215, v215, v93
	v_add_f32_e32 v215, v215, v94
	v_add_f32_e32 v215, v215, v95
	v_cvt_pk_bf16_f32 v84, v88, v89
	v_cvt_pk_bf16_f32 v85, v90, v91
	v_cvt_pk_bf16_f32 v86, v92, v93
	v_cvt_pk_bf16_f32 v87, v94, v95
	s_nop 0
	s_waitcnt lgkmcnt(0)
	v_mfma_f32_32x32x16_bf16 v[48:63], v[232:235], v[84:87], v[48:63]
	v_add_f32_e32 v183, v183, v185
	v_add_f32_e32 v187, v187, v215
	v_add_f32_e32 v183, v183, v187
	v_mov_b32_e32 v185, v183
	v_mfma_f32_32x32x16_bf16 v[32:47], v[236:239], v[84:87], v[32:47]
	v_mfma_f32_32x32x16_bf16 v[16:31], v[240:243], v[84:87], v[16:31]
	v_mfma_f32_32x32x16_bf16 v[0:15], v[244:247], v[84:87], v[0:15]
	s_nop 0
	s_nop 0
	v_permlane32_swap_b32_e32 v183, v185
	v_add_f32_e32 v183, v183, v185
	v_add_f32_e32 v189, v189, v183
	s_waitcnt vmcnt(0)
	s_barrier
	ds_read_b128 v[64:67], v173 offset:0
	ds_read_b128 v[68:71], v173 offset:4096
	s_add_u32 m0, s44, 0x6000
	ds_read_b128 v[72:75], v171 offset:0
	global_load_lds_dwordx4 v200, s[40:41]
	s_add_u32 m0, s44, 0x6400
	ds_read_b128 v[76:79], v171 offset:4096
	global_load_lds_dwordx4 v190, s[40:41]
	s_add_u32 m0, s45, 0x6000
	ds_read_b128 v[216:219], v169 offset:0
	global_load_lds_dwordx4 v192, s[42:43]
	s_add_u32 m0, s45, 0x6400
	ds_read_b128 v[220:223], v169 offset:4096
	global_load_lds_dwordx4 v194, s[42:43]
	s_add_u32 m0, s45, 0x6800
	ds_read_b128 v[224:227], v167 offset:0
	global_load_lds_dwordx4 v196, s[42:43]
	s_add_u32 m0, s45, 0x6c00
	ds_read_b128 v[228:231], v167 offset:4096
	global_load_lds_dwordx4 v198, s[42:43]
	ds_read_b128 v[232:235], v173 offset:8192
	ds_read_b128 v[236:239], v173 offset:12288
	ds_read_b128 v[240:243], v173 offset:16384
	ds_read_b128 v[244:247], v173 offset:20480
	s_add_u32 s40, s40, 0x18000
	s_addc_u32 s41, s41, 0
	s_add_u32 s42, s42, 0x80
	s_addc_u32 s43, s43, 0
	s_waitcnt lgkmcnt(11)
	v_mfma_f32_32x32x16_bf16 v[112:127], v[64:67], v[140:143], v[96:111]
	ds_read_b128 v[64:67], v171 offset:8192
	s_waitcnt lgkmcnt(11)
	v_mfma_f32_32x32x16_bf16 v[80:95], v[68:71], v[140:143], v[96:111]
	ds_read_b128 v[68:71], v171 offset:12288
	s_waitcnt lgkmcnt(11)
	v_mfma_f32_32x32x16_bf16 v[112:127], v[72:75], v[136:139], v[112:127]
	ds_read_b128 v[72:75], v171 offset:16384
	s_waitcnt lgkmcnt(11)
	v_mfma_f32_32x32x16_bf16 v[80:95], v[76:79], v[136:139], v[80:95]
	ds_read_b128 v[76:79], v171 offset:20480
	s_waitcnt lgkmcnt(11)
	v_mfma_f32_32x32x16_bf16 v[112:127], v[216:219], v[132:135], v[112:127]
	ds_read_b128 v[216:219], v169 offset:8192
	s_waitcnt lgkmcnt(11)
	v_mfma_f32_32x32x16_bf16 v[80:95], v[220:223], v[132:135], v[80:95]
	ds_read_b128 v[220:223], v169 offset:12288
	s_waitcnt lgkmcnt(11)
	v_mfma_f32_32x32x16_bf16 v[112:127], v[224:227], v[128:131], v[112:127]
	ds_read_b128 v[224:227], v169 offset:16384
	s_waitcnt lgkmcnt(11)
	v_mfma_f32_32x32x16_bf16 v[80:95], v[228:231], v[128:131], v[80:95]
	ds_read_b128 v[228:231], v169 offset:20480
	s_nop 7
	s_nop 3
	v_max3_f32 v175, v112, v113, v114
	v_max3_f32 v177, v115, v116, v117
	v_max3_f32 v179, v118, v119, v120
	v_max3_f32 v181, v121, v122, v123
	v_max3_f32 v248, v124, v125, v126
	v_max3_f32 v249, v127, v80, v81
	v_max3_f32 v250, v82, v83, v84
	v_max3_f32 v251, v85, v86, v87
	v_max3_f32 v253, v88, v89, v90
	v_max3_f32 v254, v91, v92, v93
	v_max_f32_e32 v255, v94, v95
	v_max3_f32 v175, v175, v177, v179
	v_max3_f32 v181, v181, v248, v249
	v_max3_f32 v250, v250, v251, v253
	v_max_f32_e32 v254, v254, v255
	v_max3_f32 v175, v175, v181, v250
	v_max_f32_e32 v175, v175, v254
	v_mov_b32_e32 v177, v175
	s_nop 1
	v_permlane32_swap_b32_e32 v175, v177
	v_max_f32_e32 v175, v175, v177
	v_cmp_lt_f32_e32 vcc, 0x41000000, v175
	s_cbranch_vccnz .Latt_resc_b
